# v56 + LRU3: pass-1 conv-tap loads issued before the conv bias/weight wait (one round trip at unit start)
# baseline (speedup 1.0000x reference)
; __device__ __forceinline__ void lru_pass1_unit(int cu4, const Args& a, int l, const bf16* LX, const bf16* WLRU, h2* AD, float2* LCS4, lds_t* lds, int tid, int lane, int wave, const LruGateC& gc) {
;     ...
;     { const int w8 = (tid & 31) * 8, tr = tid >> 5; float cw[4][8], cb[8];
; #pragma unroll
;         for (int j = 0; j < 4; ++j)
; #pragma unroll
;             for (int e = 0; e < 8; ++e) cw[j][e] = a.conv_w[(size_t)l * 1024 + j * 256 + w8 + e];
; #pragma unroll
;         for (int e = 0; e < 8; ++e) cb[e] = a.conv_b[l * 256 + w8 + e];
;         for (int i = 0; i < 2; ++i) { const int t = 32 * rt0 + tr + 16 * i; float acc[8];
; #pragma unroll
;             for (int e = 0; e < 8; ++e) acc[e] = cb[e];
; #pragma unroll
;             for (int j = 0; j < 4; ++j) { const int m = m0 + t + j - 2;
;                 if (m >= ms && m < me) { const v4u xv = *(const v4u*)(LX + (size_t)m * 256 + w8);
; #pragma unroll
;                     for (int e = 0; e < 4; ++e) { acc[2 * e] += bflo(xv[e]) * cw[j][2 * e]; acc[2 * e + 1] += bfhi(xv[e]) * cw[j][2 * e + 1]; } } }
.LBB0_556:
	global_load_dwordx4 v[2:5], v[52:53], off offset:16
	global_load_dwordx4 v[6:9], v[52:53], off
	global_load_dwordx4 v[26:29], v[50:51], off offset:1040
	global_load_dwordx4 v[30:33], v[50:51], off offset:1024
	global_load_dwordx4 v[18:21], v[50:51], off offset:2064
	global_load_dwordx4 v[22:25], v[50:51], off offset:2048
	global_load_dwordx4 v[10:13], v[50:51], off offset:3088
	global_load_dwordx4 v[14:17], v[50:51], off offset:3072
	global_load_dwordx4 v[34:37], v[50:51], off offset:16
	global_load_dwordx4 v[38:41], v[50:51], off
	s_and_b32 s8, s10, 3
	s_and_b64 s[18:19], s[0:1], exec
	s_cselect_b32 s9, s13, s14
	s_lshl_b32 s13, s9, 8
	s_add_i32 s13, s13, 0x8000
	s_and_b64 s[0:1], s[0:1], exec
	s_cselect_b32 s14, s15, s13
	s_lshl_b32 s13, s8, 5
	s_add_i32 s16, s12, -2
	v_add_u32_e32 v94, s13, v142
	s_add_i32 s15, s17, s14
	v_add_u32_e32 v48, s16, v94
	v_cmp_le_i32_e32 vcc, s14, v48
	v_cmp_gt_i32_e64 s[0:1], s15, v48
	s_and_b64 s[18:19], vcc, s[0:1]
	v_mov_b32_e32 v100, v48
	v_cmp_le_i32_e32 vcc, s14, v100
	v_cmp_gt_i32_e64 s[20:21], s15, v100
	v_ashrrev_i32_e32 v101, 31, v100
	s_and_b64 s[20:21], vcc, s[20:21]
	v_lshlrev_b64 v[100:101], 9, v[100:101]
	v_lshl_add_u64 v[100:101], v[54:55], 0, v[100:101]
	s_and_saveexec_b64 s[22:23], s[20:21]
	global_load_dwordx4 v[100:103], v[100:101], off
	s_mov_b64 exec, s[22:23]
	v_add_u32_e32 v104, 1, v48
	v_cmp_le_i32_e32 vcc, s14, v104
	v_cmp_gt_i32_e64 s[20:21], s15, v104
	v_ashrrev_i32_e32 v105, 31, v104
	s_and_b64 s[20:21], vcc, s[20:21]
	v_lshlrev_b64 v[104:105], 9, v[104:105]
	v_lshl_add_u64 v[104:105], v[54:55], 0, v[104:105]
	s_and_saveexec_b64 s[22:23], s[20:21]
	global_load_dwordx4 v[104:107], v[104:105], off
	s_mov_b64 exec, s[22:23]
	v_add_u32_e32 v108, s12, v94
	v_cmp_le_i32_e32 vcc, s14, v108
	v_cmp_gt_i32_e64 s[20:21], s15, v108
	v_ashrrev_i32_e32 v109, 31, v108
	s_and_b64 s[20:21], vcc, s[20:21]
	v_lshlrev_b64 v[108:109], 9, v[108:109]
	v_lshl_add_u64 v[108:109], v[54:55], 0, v[108:109]
	s_and_saveexec_b64 s[22:23], s[20:21]
	global_load_dwordx4 v[108:111], v[108:109], off
	s_mov_b64 exec, s[22:23]
	v_add_u32_e32 v130, 3, v48
	v_cmp_le_i32_e32 vcc, s14, v130
	v_cmp_gt_i32_e64 s[20:21], s15, v130
	v_ashrrev_i32_e32 v131, 31, v130
	s_and_b64 s[20:21], vcc, s[20:21]
	v_lshlrev_b64 v[130:131], 9, v[130:131]
	v_lshl_add_u64 v[130:131], v[54:55], 0, v[130:131]
	s_and_saveexec_b64 s[22:23], s[20:21]
	global_load_dwordx4 v[130:133], v[130:131], off
	s_mov_b64 exec, s[22:23]
	v_add_u32_e32 v114, 16, v48
	v_cmp_le_i32_e32 vcc, s14, v114
	v_cmp_gt_i32_e64 s[20:21], s15, v114
	v_ashrrev_i32_e32 v115, 31, v114
	s_and_b64 s[20:21], vcc, s[20:21]
	v_lshlrev_b64 v[114:115], 9, v[114:115]
	v_lshl_add_u64 v[114:115], v[54:55], 0, v[114:115]
	s_and_saveexec_b64 s[22:23], s[20:21]
	global_load_dwordx4 v[114:117], v[114:115], off
	s_mov_b64 exec, s[22:23]
	v_add_u32_e32 v118, 17, v48
	v_cmp_le_i32_e32 vcc, s14, v118
	v_cmp_gt_i32_e64 s[20:21], s15, v118
	v_ashrrev_i32_e32 v119, 31, v118
	s_and_b64 s[20:21], vcc, s[20:21]
	v_lshlrev_b64 v[118:119], 9, v[118:119]
	v_lshl_add_u64 v[118:119], v[54:55], 0, v[118:119]
	s_and_saveexec_b64 s[22:23], s[20:21]
	global_load_dwordx4 v[118:121], v[118:119], off
	s_mov_b64 exec, s[22:23]
	v_add_u32_e32 v122, s12, v94
	v_add_u32_e32 v122, 16, v122
	v_cmp_le_i32_e32 vcc, s14, v122
	v_cmp_gt_i32_e64 s[20:21], s15, v122
	v_ashrrev_i32_e32 v123, 31, v122
	s_and_b64 s[20:21], vcc, s[20:21]
	v_lshlrev_b64 v[122:123], 9, v[122:123]
	v_lshl_add_u64 v[122:123], v[54:55], 0, v[122:123]
	s_and_saveexec_b64 s[22:23], s[20:21]
	global_load_dwordx4 v[122:125], v[122:123], off
	s_mov_b64 exec, s[22:23]
	v_add_u32_e32 v126, 19, v48
	v_cmp_le_i32_e32 vcc, s14, v126
	v_cmp_gt_i32_e64 s[20:21], s15, v126
	v_ashrrev_i32_e32 v127, 31, v126
	s_and_b64 s[20:21], vcc, s[20:21]
	v_lshlrev_b64 v[126:127], 9, v[126:127]
	v_lshl_add_u64 v[126:127], v[54:55], 0, v[126:127]
	s_and_saveexec_b64 s[22:23], s[20:21]
	global_load_dwordx4 v[126:129], v[126:127], off
	s_mov_b64 exec, s[22:23]
	s_waitcnt vmcnt(0)
	v_mov_b64_e32 v[90:91], v[4:5]
	s_nop 0
	v_mov_b32_e32 v46, v6
	v_mov_b32_e32 v47, v7
	v_mov_b32_e32 v44, v8
	v_mov_b32_e32 v45, v9
	v_mov_b32_e32 v42, v2
	v_mov_b32_e32 v43, v3
	v_mov_b32_e32 v88, v4
	v_mov_b32_e32 v89, v5
	s_waitcnt vmcnt(0)
	s_and_saveexec_b64 s[0:1], s[18:19]
	s_cbranch_execz .LBB0_558
	v_ashrrev_i32_e32 v49, 31, v48
	v_lshlrev_b64 v[42:43], 9, v[48:49]
	v_lshl_add_u64 v[42:43], v[54:55], 0, v[42:43]
	s_waitcnt vmcnt(0)
	v_lshlrev_b32_e32 v90, 16, v103
	v_and_b32_e32 v91, 0xffff0000, v103
	v_lshlrev_b32_e32 v46, 16, v100
	v_and_b32_e32 v47, 0xffff0000, v100
	v_lshlrev_b32_e32 v42, 16, v101
	v_and_b32_e32 v43, 0xffff0000, v101
	v_lshlrev_b32_e32 v88, 16, v102
	v_and_b32_e32 v89, 0xffff0000, v102
	v_pk_fma_f32 v[90:91], v[36:37], v[90:91], v[4:5]
	v_pk_fma_f32 v[46:47], v[38:39], v[46:47], v[6:7]
	v_pk_fma_f32 v[44:45], v[40:41], v[42:43], v[8:9]
	v_pk_fma_f32 v[42:43], v[34:35], v[88:89], v[2:3]
	v_mov_b32_e32 v88, v90
	v_mov_b32_e32 v89, v91
